# Q/K head-norm + rope phase rewritten by hand: one wave per row, 16-byte row loads and stores staged through a per-wave LDS image, rsqrt for the norm; plus the earlier scan and epilogue edits
# speedup vs baseline: 1.0037x; 1.0037x over previous
.LBB0_858:
	s_cmp_lt_i32 s90, 6
	s_cselect_b64 s[8:9], -1, 0
	s_and_b64 s[0:1], s[8:9], s[0:1]
	s_andn2_b64 vcc, exec, s[0:1]
	s_cbranch_vccnz .LBB0_1000
	v_readlane_b32 s10, v237, 55
	v_readlane_b32 s12, v237, 0
	v_readlane_b32 s13, v237, 1
	v_readlane_b32 s18, v237, 48
	v_readlane_b32 s19, v237, 49
	s_sub_u32 s12, s12, 0x120
	s_subb_u32 s13, s13, 0
	s_load_dwordx2 s[14:15], s[12:13], 0xc8
	s_load_dwordx2 s[16:17], s[12:13], 0xd0
	s_and_b32 s11, s10, 7
	s_mul_i32 s11, s11, 0x3000
	v_lshlrev_b32_e32 v6, 4, v168
	v_add_u32_e32 v1, s11, v6
	v_lshlrev_b32_e32 v2, 1, v168
	v_add_u32_e32 v2, s11, v2
	v_lshlrev_b32_e32 v3, 2, v168
	v_and_b32_e32 v4, 31, v168
	v_lshlrev_b32_e32 v4, 2, v4
	v_lshrrev_b32_e32 v5, 4, v168
	v_lshlrev_b32_e32 v5, 9, v5
	v_and_b32_e32 v7, 15, v168
	v_lshl_add_u32 v5, v7, 4, v5
	v_cmp_gt_u32_e64 s[20:21], 32, v168
	v_mov_b32_e32 v9, 0x358637bd
	s_add_u32 s22, s88, 0x3a200000
	s_addc_u32 s23, s89, 0
	s_add_u32 s24, s88, 0x50300000
	s_addc_u32 s25, s89, 0
	s_add_u32 s26, s88, 0x3ea00000
	s_addc_u32 s27, s89, 0
	s_add_u32 s28, s88, 0x57300000
	s_addc_u32 s29, s89, 0
	s_add_u32 s30, s88, 0x180000
	s_addc_u32 s31, s89, 0
	s_add_u32 s34, s88, 0x1a0000
	s_addc_u32 s35, s89, 0
	s_waitcnt lgkmcnt(0)
	global_load_dword v10, v3, s[14:15]
	global_load_dword v11, v3, s[14:15] offset:256
	global_load_dword v12, v3, s[14:15] offset:512
	global_load_dword v13, v3, s[16:17]
	global_load_dword v14, v3, s[16:17] offset:256
	global_load_dword v15, v3, s[16:17] offset:512
.Lp5n_loop:
	s_cmp_ge_u32 s10, 0x6800
	s_cbranch_scc1 .Lp5n_done
	s_cmp_lt_u32 s10, 0x3000
	s_cbranch_scc0 .Lp5n_krow
	s_mul_i32 s36, s10, 0x1800
	s_add_u32 s36, s22, s36
	s_addc_u32 s37, s23, 0
	s_add_u32 s42, s36, 0x1000
	s_addc_u32 s43, s37, 0
	global_load_dwordx4 v[20:23], v6, s[36:37]
	global_load_dwordx4 v[24:27], v6, s[36:37] offset:1024
	global_load_dwordx4 v[28:31], v6, s[36:37] offset:2048
	global_load_dwordx4 v[32:35], v6, s[36:37] offset:3072
	global_load_dwordx4 v[36:39], v6, s[42:43]
	global_load_dwordx4 v[40:43], v6, s[42:43] offset:1024
	s_sub_u32 s38, s10, 0x2000
	s_and_b32 s38, s38, 0x3ff
	s_cmp_ge_u32 s10, 0x2000
	s_cselect_b32 s38, s38, -1
	v_mov_b32_e32 v16, 1.0
	v_mov_b32_e32 v17, 0
	s_cmp_lt_i32 s38, 0
	s_cbranch_scc1 .Lp5n_norope_q
	s_lshl_b32 s44, s38, 7
	s_add_u32 s46, s30, s44
	s_addc_u32 s47, s31, 0
	global_load_dword v16, v4, s[46:47]
	s_add_u32 s46, s34, s44
	s_addc_u32 s47, s35, 0
	global_load_dword v17, v4, s[46:47]
.Lp5n_norope_q:
	s_waitcnt vmcnt(0)
	v_xor_b32_e32 v19, 0x80000000, v17
	v_cndmask_b32_e64 v19, v17, v19, s[20:21]
	ds_write_b128 v1, v[20:23]
	ds_write_b128 v1, v[24:27] offset:1024
	ds_write_b128 v1, v[28:31] offset:2048
	ds_write_b128 v1, v[32:35] offset:3072
	ds_write_b128 v1, v[36:39] offset:4096
	ds_write_b128 v1, v[40:43] offset:5120
	s_waitcnt lgkmcnt(0)
	ds_read_u16 v44, v2 offset:0
	ds_read_u16 v45, v2 offset:128
	ds_read_u16 v46, v2 offset:256
	s_waitcnt lgkmcnt(0)
	v_lshlrev_b32_e32 v44, 16, v44
	v_lshlrev_b32_e32 v45, 16, v45
	v_lshlrev_b32_e32 v46, 16, v46
	v_mul_f32_e32 v47, v44, v44
	v_fmac_f32_e32 v47, v45, v45
	v_fmac_f32_e32 v47, v46, v46
	s_nop 1
	v_add_f32_dpp v47, v47, v47 quad_perm:[1,0,3,2] row_mask:0xf bank_mask:0xf bound_ctrl:1
	s_nop 1
	v_add_f32_dpp v47, v47, v47 quad_perm:[2,3,0,1] row_mask:0xf bank_mask:0xf bound_ctrl:1
	s_nop 1
	v_add_f32_dpp v47, v47, v47 row_half_mirror row_mask:0xf bank_mask:0xf bound_ctrl:1
	s_nop 1
	v_add_f32_dpp v47, v47, v47 row_mirror row_mask:0xf bank_mask:0xf bound_ctrl:1
	s_nop 0
	v_readlane_b32 s60, v47, 16
	v_readlane_b32 s61, v47, 48
	v_readlane_b32 s62, v47, 0
	v_readlane_b32 s63, v47, 32
	v_mov_b32_e32 v48, s60
	v_mov_b32_e32 v49, s61
	v_pk_add_f32 v[48:49], s[62:63], v[48:49]
	s_nop 0
	v_add_f32_e32 v47, v48, v49
	v_fmamk_f32 v47, v47, 0x3baaaaab, v9
	v_rsq_f32_e32 v47, v47
	s_nop 0
	v_mul_f32_e32 v44, v44, v47
	v_mul_f32_e32 v45, v45, v47
	v_mul_f32_e32 v46, v46, v47
	v_mul_f32_e32 v44, v44, v10
	v_mul_f32_e32 v45, v45, v11
	v_mul_f32_e32 v46, v46, v12
	v_mov_b32_e32 v48, v46
	s_nop 1
	v_permlane32_swap_b32_e32 v48, v46
	s_nop 1
	v_cndmask_b32_e64 v50, v46, v48, s[20:21]
	v_cndmask_b32_e64 v51, v48, v46, s[20:21]
	v_mul_f32_e32 v46, v50, v16
	v_fmac_f32_e32 v46, v51, v19
	v_cvt_pk_bf16_f32 v44, v44, v45
	v_cvt_pk_bf16_f32 v46, v46, v46
	ds_write_b16 v2, v44 offset:6144
	ds_write_b16_d16_hi v2, v44 offset:6272
	ds_write_b16 v2, v46 offset:6400
	ds_read_u16 v44, v2 offset:384
	ds_read_u16 v45, v2 offset:512
	ds_read_u16 v46, v2 offset:640
	s_waitcnt lgkmcnt(0)
	v_lshlrev_b32_e32 v44, 16, v44
	v_lshlrev_b32_e32 v45, 16, v45
	v_lshlrev_b32_e32 v46, 16, v46
	v_mul_f32_e32 v47, v44, v44
	v_fmac_f32_e32 v47, v45, v45
	v_fmac_f32_e32 v47, v46, v46
	s_nop 1
	v_add_f32_dpp v47, v47, v47 quad_perm:[1,0,3,2] row_mask:0xf bank_mask:0xf bound_ctrl:1
	s_nop 1
	v_add_f32_dpp v47, v47, v47 quad_perm:[2,3,0,1] row_mask:0xf bank_mask:0xf bound_ctrl:1
	s_nop 1
	v_add_f32_dpp v47, v47, v47 row_half_mirror row_mask:0xf bank_mask:0xf bound_ctrl:1
	s_nop 1
	v_add_f32_dpp v47, v47, v47 row_mirror row_mask:0xf bank_mask:0xf bound_ctrl:1
	s_nop 0
	v_readlane_b32 s60, v47, 16
	v_readlane_b32 s61, v47, 48
	v_readlane_b32 s62, v47, 0
	v_readlane_b32 s63, v47, 32
	v_mov_b32_e32 v48, s60
	v_mov_b32_e32 v49, s61
	v_pk_add_f32 v[48:49], s[62:63], v[48:49]
	s_nop 0
	v_add_f32_e32 v47, v48, v49
	v_fmamk_f32 v47, v47, 0x3baaaaab, v9
	v_rsq_f32_e32 v47, v47
	s_nop 0
	v_mul_f32_e32 v44, v44, v47
	v_mul_f32_e32 v45, v45, v47
	v_mul_f32_e32 v46, v46, v47
	v_mul_f32_e32 v44, v44, v10
	v_mul_f32_e32 v45, v45, v11
	v_mul_f32_e32 v46, v46, v12
	v_mov_b32_e32 v48, v46
	s_nop 1
	v_permlane32_swap_b32_e32 v48, v46
	s_nop 1
	v_cndmask_b32_e64 v50, v46, v48, s[20:21]
	v_cndmask_b32_e64 v51, v48, v46, s[20:21]
	v_mul_f32_e32 v46, v50, v16
	v_fmac_f32_e32 v46, v51, v19
	v_cvt_pk_bf16_f32 v44, v44, v45
	v_cvt_pk_bf16_f32 v46, v46, v46
	ds_write_b16 v2, v44 offset:6528
	ds_write_b16_d16_hi v2, v44 offset:6656
	ds_write_b16 v2, v46 offset:6784
	ds_read_u16 v44, v2 offset:768
	ds_read_u16 v45, v2 offset:896
	ds_read_u16 v46, v2 offset:1024
	s_waitcnt lgkmcnt(0)
	v_lshlrev_b32_e32 v44, 16, v44
	v_lshlrev_b32_e32 v45, 16, v45
	v_lshlrev_b32_e32 v46, 16, v46
	v_mul_f32_e32 v47, v44, v44
	v_fmac_f32_e32 v47, v45, v45
	v_fmac_f32_e32 v47, v46, v46
	s_nop 1
	v_add_f32_dpp v47, v47, v47 quad_perm:[1,0,3,2] row_mask:0xf bank_mask:0xf bound_ctrl:1
	s_nop 1
	v_add_f32_dpp v47, v47, v47 quad_perm:[2,3,0,1] row_mask:0xf bank_mask:0xf bound_ctrl:1
	s_nop 1
	v_add_f32_dpp v47, v47, v47 row_half_mirror row_mask:0xf bank_mask:0xf bound_ctrl:1
	s_nop 1
	v_add_f32_dpp v47, v47, v47 row_mirror row_mask:0xf bank_mask:0xf bound_ctrl:1
	s_nop 0
	v_readlane_b32 s60, v47, 16
	v_readlane_b32 s61, v47, 48
	v_readlane_b32 s62, v47, 0
	v_readlane_b32 s63, v47, 32
	v_mov_b32_e32 v48, s60
	v_mov_b32_e32 v49, s61
	v_pk_add_f32 v[48:49], s[62:63], v[48:49]
	s_nop 0
	v_add_f32_e32 v47, v48, v49
	v_fmamk_f32 v47, v47, 0x3baaaaab, v9
	v_rsq_f32_e32 v47, v47
	s_nop 0
	v_mul_f32_e32 v44, v44, v47
	v_mul_f32_e32 v45, v45, v47
	v_mul_f32_e32 v46, v46, v47
	v_mul_f32_e32 v44, v44, v10
	v_mul_f32_e32 v45, v45, v11
	v_mul_f32_e32 v46, v46, v12
	v_mov_b32_e32 v48, v46
	s_nop 1
	v_permlane32_swap_b32_e32 v48, v46
	s_nop 1
	v_cndmask_b32_e64 v50, v46, v48, s[20:21]
	v_cndmask_b32_e64 v51, v48, v46, s[20:21]
	v_mul_f32_e32 v46, v50, v16
	v_fmac_f32_e32 v46, v51, v19
	v_cvt_pk_bf16_f32 v44, v44, v45
	v_cvt_pk_bf16_f32 v46, v46, v46
	ds_write_b16 v2, v44 offset:6912
	ds_write_b16_d16_hi v2, v44 offset:7040
	ds_write_b16 v2, v46 offset:7168
	ds_read_u16 v44, v2 offset:1152
	ds_read_u16 v45, v2 offset:1280
	ds_read_u16 v46, v2 offset:1408
	s_waitcnt lgkmcnt(0)
	v_lshlrev_b32_e32 v44, 16, v44
	v_lshlrev_b32_e32 v45, 16, v45
	v_lshlrev_b32_e32 v46, 16, v46
	v_mul_f32_e32 v47, v44, v44
	v_fmac_f32_e32 v47, v45, v45
	v_fmac_f32_e32 v47, v46, v46
	s_nop 1
	v_add_f32_dpp v47, v47, v47 quad_perm:[1,0,3,2] row_mask:0xf bank_mask:0xf bound_ctrl:1
	s_nop 1
	v_add_f32_dpp v47, v47, v47 quad_perm:[2,3,0,1] row_mask:0xf bank_mask:0xf bound_ctrl:1
	s_nop 1
	v_add_f32_dpp v47, v47, v47 row_half_mirror row_mask:0xf bank_mask:0xf bound_ctrl:1
	s_nop 1
	v_add_f32_dpp v47, v47, v47 row_mirror row_mask:0xf bank_mask:0xf bound_ctrl:1
	s_nop 0
	v_readlane_b32 s60, v47, 16
	v_readlane_b32 s61, v47, 48
	v_readlane_b32 s62, v47, 0
	v_readlane_b32 s63, v47, 32
	v_mov_b32_e32 v48, s60
	v_mov_b32_e32 v49, s61
	v_pk_add_f32 v[48:49], s[62:63], v[48:49]
	s_nop 0
	v_add_f32_e32 v47, v48, v49
	v_fmamk_f32 v47, v47, 0x3baaaaab, v9
	v_rsq_f32_e32 v47, v47
	s_nop 0
	v_mul_f32_e32 v44, v44, v47
	v_mul_f32_e32 v45, v45, v47
	v_mul_f32_e32 v46, v46, v47
	v_mul_f32_e32 v44, v44, v10
	v_mul_f32_e32 v45, v45, v11
	v_mul_f32_e32 v46, v46, v12
	v_mov_b32_e32 v48, v46
	s_nop 1
	v_permlane32_swap_b32_e32 v48, v46
	s_nop 1
	v_cndmask_b32_e64 v50, v46, v48, s[20:21]
	v_cndmask_b32_e64 v51, v48, v46, s[20:21]
	v_mul_f32_e32 v46, v50, v16
	v_fmac_f32_e32 v46, v51, v19
	v_cvt_pk_bf16_f32 v44, v44, v45
	v_cvt_pk_bf16_f32 v46, v46, v46
	ds_write_b16 v2, v44 offset:7296
	ds_write_b16_d16_hi v2, v44 offset:7424
	ds_write_b16 v2, v46 offset:7552
	ds_read_u16 v44, v2 offset:1536
	ds_read_u16 v45, v2 offset:1664
	ds_read_u16 v46, v2 offset:1792
	s_waitcnt lgkmcnt(0)
	v_lshlrev_b32_e32 v44, 16, v44
	v_lshlrev_b32_e32 v45, 16, v45
	v_lshlrev_b32_e32 v46, 16, v46
	v_mul_f32_e32 v47, v44, v44
	v_fmac_f32_e32 v47, v45, v45
	v_fmac_f32_e32 v47, v46, v46
	s_nop 1
	v_add_f32_dpp v47, v47, v47 quad_perm:[1,0,3,2] row_mask:0xf bank_mask:0xf bound_ctrl:1
	s_nop 1
	v_add_f32_dpp v47, v47, v47 quad_perm:[2,3,0,1] row_mask:0xf bank_mask:0xf bound_ctrl:1
	s_nop 1
	v_add_f32_dpp v47, v47, v47 row_half_mirror row_mask:0xf bank_mask:0xf bound_ctrl:1
	s_nop 1
	v_add_f32_dpp v47, v47, v47 row_mirror row_mask:0xf bank_mask:0xf bound_ctrl:1
	s_nop 0
	v_readlane_b32 s60, v47, 16
	v_readlane_b32 s61, v47, 48
	v_readlane_b32 s62, v47, 0
	v_readlane_b32 s63, v47, 32
	v_mov_b32_e32 v48, s60
	v_mov_b32_e32 v49, s61
	v_pk_add_f32 v[48:49], s[62:63], v[48:49]
	s_nop 0
	v_add_f32_e32 v47, v48, v49
	v_fmamk_f32 v47, v47, 0x3baaaaab, v9
	v_rsq_f32_e32 v47, v47
	s_nop 0
	v_mul_f32_e32 v44, v44, v47
	v_mul_f32_e32 v45, v45, v47
	v_mul_f32_e32 v46, v46, v47
	v_mul_f32_e32 v44, v44, v10
	v_mul_f32_e32 v45, v45, v11
	v_mul_f32_e32 v46, v46, v12
	v_mov_b32_e32 v48, v46
	s_nop 1
	v_permlane32_swap_b32_e32 v48, v46
	s_nop 1
	v_cndmask_b32_e64 v50, v46, v48, s[20:21]
	v_cndmask_b32_e64 v51, v48, v46, s[20:21]
	v_mul_f32_e32 v46, v50, v16
	v_fmac_f32_e32 v46, v51, v19
	v_cvt_pk_bf16_f32 v44, v44, v45
	v_cvt_pk_bf16_f32 v46, v46, v46
	ds_write_b16 v2, v44 offset:7680
	ds_write_b16_d16_hi v2, v44 offset:7808
	ds_write_b16 v2, v46 offset:7936
	ds_read_u16 v44, v2 offset:1920
	ds_read_u16 v45, v2 offset:2048
	ds_read_u16 v46, v2 offset:2176
	s_waitcnt lgkmcnt(0)
	v_lshlrev_b32_e32 v44, 16, v44
	v_lshlrev_b32_e32 v45, 16, v45
	v_lshlrev_b32_e32 v46, 16, v46
	v_mul_f32_e32 v47, v44, v44
	v_fmac_f32_e32 v47, v45, v45
	v_fmac_f32_e32 v47, v46, v46
	s_nop 1
	v_add_f32_dpp v47, v47, v47 quad_perm:[1,0,3,2] row_mask:0xf bank_mask:0xf bound_ctrl:1
	s_nop 1
	v_add_f32_dpp v47, v47, v47 quad_perm:[2,3,0,1] row_mask:0xf bank_mask:0xf bound_ctrl:1
	s_nop 1
	v_add_f32_dpp v47, v47, v47 row_half_mirror row_mask:0xf bank_mask:0xf bound_ctrl:1
	s_nop 1
	v_add_f32_dpp v47, v47, v47 row_mirror row_mask:0xf bank_mask:0xf bound_ctrl:1
	s_nop 0
	v_readlane_b32 s60, v47, 16
	v_readlane_b32 s61, v47, 48
	v_readlane_b32 s62, v47, 0
	v_readlane_b32 s63, v47, 32
	v_mov_b32_e32 v48, s60
	v_mov_b32_e32 v49, s61
	v_pk_add_f32 v[48:49], s[62:63], v[48:49]
	s_nop 0
	v_add_f32_e32 v47, v48, v49
	v_fmamk_f32 v47, v47, 0x3baaaaab, v9
	v_rsq_f32_e32 v47, v47
	s_nop 0
	v_mul_f32_e32 v44, v44, v47
	v_mul_f32_e32 v45, v45, v47
	v_mul_f32_e32 v46, v46, v47
	v_mul_f32_e32 v44, v44, v10
	v_mul_f32_e32 v45, v45, v11
	v_mul_f32_e32 v46, v46, v12
	v_mov_b32_e32 v48, v46
	s_nop 1
	v_permlane32_swap_b32_e32 v48, v46
	s_nop 1
	v_cndmask_b32_e64 v50, v46, v48, s[20:21]
	v_cndmask_b32_e64 v51, v48, v46, s[20:21]
	v_mul_f32_e32 v46, v50, v16
	v_fmac_f32_e32 v46, v51, v19
	v_cvt_pk_bf16_f32 v44, v44, v45
	v_cvt_pk_bf16_f32 v46, v46, v46
	ds_write_b16 v2, v44 offset:8064
	ds_write_b16_d16_hi v2, v44 offset:8192
	ds_write_b16 v2, v46 offset:8320
	ds_read_u16 v44, v2 offset:2304
	ds_read_u16 v45, v2 offset:2432
	ds_read_u16 v46, v2 offset:2560
	s_waitcnt lgkmcnt(0)
	v_lshlrev_b32_e32 v44, 16, v44
	v_lshlrev_b32_e32 v45, 16, v45
	v_lshlrev_b32_e32 v46, 16, v46
	v_mul_f32_e32 v47, v44, v44
	v_fmac_f32_e32 v47, v45, v45
	v_fmac_f32_e32 v47, v46, v46
	s_nop 1
	v_add_f32_dpp v47, v47, v47 quad_perm:[1,0,3,2] row_mask:0xf bank_mask:0xf bound_ctrl:1
	s_nop 1
	v_add_f32_dpp v47, v47, v47 quad_perm:[2,3,0,1] row_mask:0xf bank_mask:0xf bound_ctrl:1
	s_nop 1
	v_add_f32_dpp v47, v47, v47 row_half_mirror row_mask:0xf bank_mask:0xf bound_ctrl:1
	s_nop 1
	v_add_f32_dpp v47, v47, v47 row_mirror row_mask:0xf bank_mask:0xf bound_ctrl:1
	s_nop 0
	v_readlane_b32 s60, v47, 16
	v_readlane_b32 s61, v47, 48
	v_readlane_b32 s62, v47, 0
	v_readlane_b32 s63, v47, 32
	v_mov_b32_e32 v48, s60
	v_mov_b32_e32 v49, s61
	v_pk_add_f32 v[48:49], s[62:63], v[48:49]
	s_nop 0
	v_add_f32_e32 v47, v48, v49
	v_fmamk_f32 v47, v47, 0x3baaaaab, v9
	v_rsq_f32_e32 v47, v47
	s_nop 0
	v_mul_f32_e32 v44, v44, v47
	v_mul_f32_e32 v45, v45, v47
	v_mul_f32_e32 v46, v46, v47
	v_mul_f32_e32 v44, v44, v10
	v_mul_f32_e32 v45, v45, v11
	v_mul_f32_e32 v46, v46, v12
	v_mov_b32_e32 v48, v46
	s_nop 1
	v_permlane32_swap_b32_e32 v48, v46
	s_nop 1
	v_cndmask_b32_e64 v50, v46, v48, s[20:21]
	v_cndmask_b32_e64 v51, v48, v46, s[20:21]
	v_mul_f32_e32 v46, v50, v16
	v_fmac_f32_e32 v46, v51, v19
	v_cvt_pk_bf16_f32 v44, v44, v45
	v_cvt_pk_bf16_f32 v46, v46, v46
	ds_write_b16 v2, v44 offset:8448
	ds_write_b16_d16_hi v2, v44 offset:8576
	ds_write_b16 v2, v46 offset:8704
	ds_read_u16 v44, v2 offset:2688
	ds_read_u16 v45, v2 offset:2816
	ds_read_u16 v46, v2 offset:2944
	s_waitcnt lgkmcnt(0)
	v_lshlrev_b32_e32 v44, 16, v44
	v_lshlrev_b32_e32 v45, 16, v45
	v_lshlrev_b32_e32 v46, 16, v46
	v_mul_f32_e32 v47, v44, v44
	v_fmac_f32_e32 v47, v45, v45
	v_fmac_f32_e32 v47, v46, v46
	s_nop 1
	v_add_f32_dpp v47, v47, v47 quad_perm:[1,0,3,2] row_mask:0xf bank_mask:0xf bound_ctrl:1
	s_nop 1
	v_add_f32_dpp v47, v47, v47 quad_perm:[2,3,0,1] row_mask:0xf bank_mask:0xf bound_ctrl:1
	s_nop 1
	v_add_f32_dpp v47, v47, v47 row_half_mirror row_mask:0xf bank_mask:0xf bound_ctrl:1
	s_nop 1
	v_add_f32_dpp v47, v47, v47 row_mirror row_mask:0xf bank_mask:0xf bound_ctrl:1
	s_nop 0
	v_readlane_b32 s60, v47, 16
	v_readlane_b32 s61, v47, 48
	v_readlane_b32 s62, v47, 0
	v_readlane_b32 s63, v47, 32
	v_mov_b32_e32 v48, s60
	v_mov_b32_e32 v49, s61
	v_pk_add_f32 v[48:49], s[62:63], v[48:49]
	s_nop 0
	v_add_f32_e32 v47, v48, v49
	v_fmamk_f32 v47, v47, 0x3baaaaab, v9
	v_rsq_f32_e32 v47, v47
	s_nop 0
	v_mul_f32_e32 v44, v44, v47
	v_mul_f32_e32 v45, v45, v47
	v_mul_f32_e32 v46, v46, v47
	v_mul_f32_e32 v44, v44, v10
	v_mul_f32_e32 v45, v45, v11
	v_mul_f32_e32 v46, v46, v12
	v_mov_b32_e32 v48, v46
	s_nop 1
	v_permlane32_swap_b32_e32 v48, v46
	s_nop 1
	v_cndmask_b32_e64 v50, v46, v48, s[20:21]
	v_cndmask_b32_e64 v51, v48, v46, s[20:21]
	v_mul_f32_e32 v46, v50, v16
	v_fmac_f32_e32 v46, v51, v19
	v_cvt_pk_bf16_f32 v44, v44, v45
	v_cvt_pk_bf16_f32 v46, v46, v46
	ds_write_b16 v2, v44 offset:8832
	ds_write_b16_d16_hi v2, v44 offset:8960
	ds_write_b16 v2, v46 offset:9088
	ds_read_u16 v44, v2 offset:3072
	ds_read_u16 v45, v2 offset:3200
	ds_read_u16 v46, v2 offset:3328
	s_waitcnt lgkmcnt(0)
	v_lshlrev_b32_e32 v44, 16, v44
	v_lshlrev_b32_e32 v45, 16, v45
	v_lshlrev_b32_e32 v46, 16, v46
	v_mul_f32_e32 v47, v44, v44
	v_fmac_f32_e32 v47, v45, v45
	v_fmac_f32_e32 v47, v46, v46
	s_nop 1
	v_add_f32_dpp v47, v47, v47 quad_perm:[1,0,3,2] row_mask:0xf bank_mask:0xf bound_ctrl:1
	s_nop 1
	v_add_f32_dpp v47, v47, v47 quad_perm:[2,3,0,1] row_mask:0xf bank_mask:0xf bound_ctrl:1
	s_nop 1
	v_add_f32_dpp v47, v47, v47 row_half_mirror row_mask:0xf bank_mask:0xf bound_ctrl:1
	s_nop 1
	v_add_f32_dpp v47, v47, v47 row_mirror row_mask:0xf bank_mask:0xf bound_ctrl:1
	s_nop 0
	v_readlane_b32 s60, v47, 16
	v_readlane_b32 s61, v47, 48
	v_readlane_b32 s62, v47, 0
	v_readlane_b32 s63, v47, 32
	v_mov_b32_e32 v48, s60
	v_mov_b32_e32 v49, s61
	v_pk_add_f32 v[48:49], s[62:63], v[48:49]
	s_nop 0
	v_add_f32_e32 v47, v48, v49
	v_fmamk_f32 v47, v47, 0x3baaaaab, v9
	v_rsq_f32_e32 v47, v47
	s_nop 0
	v_mul_f32_e32 v44, v44, v47
	v_mul_f32_e32 v45, v45, v47
	v_mul_f32_e32 v46, v46, v47
	v_mul_f32_e32 v44, v44, v10
	v_mul_f32_e32 v45, v45, v11
	v_mul_f32_e32 v46, v46, v12
	v_mov_b32_e32 v48, v46
	s_nop 1
	v_permlane32_swap_b32_e32 v48, v46
	s_nop 1
	v_cndmask_b32_e64 v50, v46, v48, s[20:21]
	v_cndmask_b32_e64 v51, v48, v46, s[20:21]
	v_mul_f32_e32 v46, v50, v16
	v_fmac_f32_e32 v46, v51, v19
	v_cvt_pk_bf16_f32 v44, v44, v45
	v_cvt_pk_bf16_f32 v46, v46, v46
	ds_write_b16 v2, v44 offset:9216
	ds_write_b16_d16_hi v2, v44 offset:9344
	ds_write_b16 v2, v46 offset:9472
	ds_read_u16 v44, v2 offset:3456
	ds_read_u16 v45, v2 offset:3584
	ds_read_u16 v46, v2 offset:3712
	s_waitcnt lgkmcnt(0)
	v_lshlrev_b32_e32 v44, 16, v44
	v_lshlrev_b32_e32 v45, 16, v45
	v_lshlrev_b32_e32 v46, 16, v46
	v_mul_f32_e32 v47, v44, v44
	v_fmac_f32_e32 v47, v45, v45
	v_fmac_f32_e32 v47, v46, v46
	s_nop 1
	v_add_f32_dpp v47, v47, v47 quad_perm:[1,0,3,2] row_mask:0xf bank_mask:0xf bound_ctrl:1
	s_nop 1
	v_add_f32_dpp v47, v47, v47 quad_perm:[2,3,0,1] row_mask:0xf bank_mask:0xf bound_ctrl:1
	s_nop 1
	v_add_f32_dpp v47, v47, v47 row_half_mirror row_mask:0xf bank_mask:0xf bound_ctrl:1
	s_nop 1
	v_add_f32_dpp v47, v47, v47 row_mirror row_mask:0xf bank_mask:0xf bound_ctrl:1
	s_nop 0
	v_readlane_b32 s60, v47, 16
	v_readlane_b32 s61, v47, 48
	v_readlane_b32 s62, v47, 0
	v_readlane_b32 s63, v47, 32
	v_mov_b32_e32 v48, s60
	v_mov_b32_e32 v49, s61
	v_pk_add_f32 v[48:49], s[62:63], v[48:49]
	s_nop 0
	v_add_f32_e32 v47, v48, v49
	v_fmamk_f32 v47, v47, 0x3baaaaab, v9
	v_rsq_f32_e32 v47, v47
	s_nop 0
	v_mul_f32_e32 v44, v44, v47
	v_mul_f32_e32 v45, v45, v47
	v_mul_f32_e32 v46, v46, v47
	v_mul_f32_e32 v44, v44, v10
	v_mul_f32_e32 v45, v45, v11
	v_mul_f32_e32 v46, v46, v12
	v_mov_b32_e32 v48, v46
	s_nop 1
	v_permlane32_swap_b32_e32 v48, v46
	s_nop 1
	v_cndmask_b32_e64 v50, v46, v48, s[20:21]
	v_cndmask_b32_e64 v51, v48, v46, s[20:21]
	v_mul_f32_e32 v46, v50, v16
	v_fmac_f32_e32 v46, v51, v19
	v_cvt_pk_bf16_f32 v44, v44, v45
	v_cvt_pk_bf16_f32 v46, v46, v46
	ds_write_b16 v2, v44 offset:9600
	ds_write_b16_d16_hi v2, v44 offset:9728
	ds_write_b16 v2, v46 offset:9856
	ds_read_u16 v44, v2 offset:3840
	ds_read_u16 v45, v2 offset:3968
	ds_read_u16 v46, v2 offset:4096
	s_waitcnt lgkmcnt(0)
	v_lshlrev_b32_e32 v44, 16, v44
	v_lshlrev_b32_e32 v45, 16, v45
	v_lshlrev_b32_e32 v46, 16, v46
	v_mul_f32_e32 v47, v44, v44
	v_fmac_f32_e32 v47, v45, v45
	v_fmac_f32_e32 v47, v46, v46
	s_nop 1
	v_add_f32_dpp v47, v47, v47 quad_perm:[1,0,3,2] row_mask:0xf bank_mask:0xf bound_ctrl:1
	s_nop 1
	v_add_f32_dpp v47, v47, v47 quad_perm:[2,3,0,1] row_mask:0xf bank_mask:0xf bound_ctrl:1
	s_nop 1
	v_add_f32_dpp v47, v47, v47 row_half_mirror row_mask:0xf bank_mask:0xf bound_ctrl:1
	s_nop 1
	v_add_f32_dpp v47, v47, v47 row_mirror row_mask:0xf bank_mask:0xf bound_ctrl:1
	s_nop 0
	v_readlane_b32 s60, v47, 16
	v_readlane_b32 s61, v47, 48
	v_readlane_b32 s62, v47, 0
	v_readlane_b32 s63, v47, 32
	v_mov_b32_e32 v48, s60
	v_mov_b32_e32 v49, s61
	v_pk_add_f32 v[48:49], s[62:63], v[48:49]
	s_nop 0
	v_add_f32_e32 v47, v48, v49
	v_fmamk_f32 v47, v47, 0x3baaaaab, v9
	v_rsq_f32_e32 v47, v47
	s_nop 0
	v_mul_f32_e32 v44, v44, v47
	v_mul_f32_e32 v45, v45, v47
	v_mul_f32_e32 v46, v46, v47
	v_mul_f32_e32 v44, v44, v10
	v_mul_f32_e32 v45, v45, v11
	v_mul_f32_e32 v46, v46, v12
	v_mov_b32_e32 v48, v46
	s_nop 1
	v_permlane32_swap_b32_e32 v48, v46
	s_nop 1
	v_cndmask_b32_e64 v50, v46, v48, s[20:21]
	v_cndmask_b32_e64 v51, v48, v46, s[20:21]
	v_mul_f32_e32 v46, v50, v16
	v_fmac_f32_e32 v46, v51, v19
	v_cvt_pk_bf16_f32 v44, v44, v45
	v_cvt_pk_bf16_f32 v46, v46, v46
	ds_write_b16 v2, v44 offset:9984
	ds_write_b16_d16_hi v2, v44 offset:10112
	ds_write_b16 v2, v46 offset:10240
	ds_read_u16 v44, v2 offset:4224
	ds_read_u16 v45, v2 offset:4352
	ds_read_u16 v46, v2 offset:4480
	s_waitcnt lgkmcnt(0)
	v_lshlrev_b32_e32 v44, 16, v44
	v_lshlrev_b32_e32 v45, 16, v45
	v_lshlrev_b32_e32 v46, 16, v46
	v_mul_f32_e32 v47, v44, v44
	v_fmac_f32_e32 v47, v45, v45
	v_fmac_f32_e32 v47, v46, v46
	s_nop 1
	v_add_f32_dpp v47, v47, v47 quad_perm:[1,0,3,2] row_mask:0xf bank_mask:0xf bound_ctrl:1
	s_nop 1
	v_add_f32_dpp v47, v47, v47 quad_perm:[2,3,0,1] row_mask:0xf bank_mask:0xf bound_ctrl:1
	s_nop 1
	v_add_f32_dpp v47, v47, v47 row_half_mirror row_mask:0xf bank_mask:0xf bound_ctrl:1
	s_nop 1
	v_add_f32_dpp v47, v47, v47 row_mirror row_mask:0xf bank_mask:0xf bound_ctrl:1
	s_nop 0
	v_readlane_b32 s60, v47, 16
	v_readlane_b32 s61, v47, 48
	v_readlane_b32 s62, v47, 0
	v_readlane_b32 s63, v47, 32
	v_mov_b32_e32 v48, s60
	v_mov_b32_e32 v49, s61
	v_pk_add_f32 v[48:49], s[62:63], v[48:49]
	s_nop 0
	v_add_f32_e32 v47, v48, v49
	v_fmamk_f32 v47, v47, 0x3baaaaab, v9
	v_rsq_f32_e32 v47, v47
	s_nop 0
	v_mul_f32_e32 v44, v44, v47
	v_mul_f32_e32 v45, v45, v47
	v_mul_f32_e32 v46, v46, v47
	v_mul_f32_e32 v44, v44, v10
	v_mul_f32_e32 v45, v45, v11
	v_mul_f32_e32 v46, v46, v12
	v_mov_b32_e32 v48, v46
	s_nop 1
	v_permlane32_swap_b32_e32 v48, v46
	s_nop 1
	v_cndmask_b32_e64 v50, v46, v48, s[20:21]
	v_cndmask_b32_e64 v51, v48, v46, s[20:21]
	v_mul_f32_e32 v46, v50, v16
	v_fmac_f32_e32 v46, v51, v19
	v_cvt_pk_bf16_f32 v44, v44, v45
	v_cvt_pk_bf16_f32 v46, v46, v46
	ds_write_b16 v2, v44 offset:10368
	ds_write_b16_d16_hi v2, v44 offset:10496
	ds_write_b16 v2, v46 offset:10624
	ds_read_u16 v44, v2 offset:4608
	ds_read_u16 v45, v2 offset:4736
	ds_read_u16 v46, v2 offset:4864
	s_waitcnt lgkmcnt(0)
	v_lshlrev_b32_e32 v44, 16, v44
	v_lshlrev_b32_e32 v45, 16, v45
	v_lshlrev_b32_e32 v46, 16, v46
	v_mul_f32_e32 v47, v44, v44
	v_fmac_f32_e32 v47, v45, v45
	v_fmac_f32_e32 v47, v46, v46
	s_nop 1
	v_add_f32_dpp v47, v47, v47 quad_perm:[1,0,3,2] row_mask:0xf bank_mask:0xf bound_ctrl:1
	s_nop 1
	v_add_f32_dpp v47, v47, v47 quad_perm:[2,3,0,1] row_mask:0xf bank_mask:0xf bound_ctrl:1
	s_nop 1
	v_add_f32_dpp v47, v47, v47 row_half_mirror row_mask:0xf bank_mask:0xf bound_ctrl:1
	s_nop 1
	v_add_f32_dpp v47, v47, v47 row_mirror row_mask:0xf bank_mask:0xf bound_ctrl:1
	s_nop 0
	v_readlane_b32 s60, v47, 16
	v_readlane_b32 s61, v47, 48
	v_readlane_b32 s62, v47, 0
	v_readlane_b32 s63, v47, 32
	v_mov_b32_e32 v48, s60
	v_mov_b32_e32 v49, s61
	v_pk_add_f32 v[48:49], s[62:63], v[48:49]
	s_nop 0
	v_add_f32_e32 v47, v48, v49
	v_fmamk_f32 v47, v47, 0x3baaaaab, v9
	v_rsq_f32_e32 v47, v47
	s_nop 0
	v_mul_f32_e32 v44, v44, v47
	v_mul_f32_e32 v45, v45, v47
	v_mul_f32_e32 v46, v46, v47
	v_mul_f32_e32 v44, v44, v10
	v_mul_f32_e32 v45, v45, v11
	v_mul_f32_e32 v46, v46, v12
	v_mov_b32_e32 v48, v46
	s_nop 1
	v_permlane32_swap_b32_e32 v48, v46
	s_nop 1
	v_cndmask_b32_e64 v50, v46, v48, s[20:21]
	v_cndmask_b32_e64 v51, v48, v46, s[20:21]
	v_mul_f32_e32 v46, v50, v16
	v_fmac_f32_e32 v46, v51, v19
	v_cvt_pk_bf16_f32 v44, v44, v45
	v_cvt_pk_bf16_f32 v46, v46, v46
	ds_write_b16 v2, v44 offset:10752
	ds_write_b16_d16_hi v2, v44 offset:10880
	ds_write_b16 v2, v46 offset:11008
	ds_read_u16 v44, v2 offset:4992
	ds_read_u16 v45, v2 offset:5120
	ds_read_u16 v46, v2 offset:5248
	s_waitcnt lgkmcnt(0)
	v_lshlrev_b32_e32 v44, 16, v44
	v_lshlrev_b32_e32 v45, 16, v45
	v_lshlrev_b32_e32 v46, 16, v46
	v_mul_f32_e32 v47, v44, v44
	v_fmac_f32_e32 v47, v45, v45
	v_fmac_f32_e32 v47, v46, v46
	s_nop 1
	v_add_f32_dpp v47, v47, v47 quad_perm:[1,0,3,2] row_mask:0xf bank_mask:0xf bound_ctrl:1
	s_nop 1
	v_add_f32_dpp v47, v47, v47 quad_perm:[2,3,0,1] row_mask:0xf bank_mask:0xf bound_ctrl:1
	s_nop 1
	v_add_f32_dpp v47, v47, v47 row_half_mirror row_mask:0xf bank_mask:0xf bound_ctrl:1
	s_nop 1
	v_add_f32_dpp v47, v47, v47 row_mirror row_mask:0xf bank_mask:0xf bound_ctrl:1
	s_nop 0
	v_readlane_b32 s60, v47, 16
	v_readlane_b32 s61, v47, 48
	v_readlane_b32 s62, v47, 0
	v_readlane_b32 s63, v47, 32
	v_mov_b32_e32 v48, s60
	v_mov_b32_e32 v49, s61
	v_pk_add_f32 v[48:49], s[62:63], v[48:49]
	s_nop 0
	v_add_f32_e32 v47, v48, v49
	v_fmamk_f32 v47, v47, 0x3baaaaab, v9
	v_rsq_f32_e32 v47, v47
	s_nop 0
	v_mul_f32_e32 v44, v44, v47
	v_mul_f32_e32 v45, v45, v47
	v_mul_f32_e32 v46, v46, v47
	v_mul_f32_e32 v44, v44, v10
	v_mul_f32_e32 v45, v45, v11
	v_mul_f32_e32 v46, v46, v12
	v_mov_b32_e32 v48, v46
	s_nop 1
	v_permlane32_swap_b32_e32 v48, v46
	s_nop 1
	v_cndmask_b32_e64 v50, v46, v48, s[20:21]
	v_cndmask_b32_e64 v51, v48, v46, s[20:21]
	v_mul_f32_e32 v46, v50, v16
	v_fmac_f32_e32 v46, v51, v19
	v_cvt_pk_bf16_f32 v44, v44, v45
	v_cvt_pk_bf16_f32 v46, v46, v46
	ds_write_b16 v2, v44 offset:11136
	ds_write_b16_d16_hi v2, v44 offset:11264
	ds_write_b16 v2, v46 offset:11392
	ds_read_u16 v44, v2 offset:5376
	ds_read_u16 v45, v2 offset:5504
	ds_read_u16 v46, v2 offset:5632
	s_waitcnt lgkmcnt(0)
	v_lshlrev_b32_e32 v44, 16, v44
	v_lshlrev_b32_e32 v45, 16, v45
	v_lshlrev_b32_e32 v46, 16, v46
	v_mul_f32_e32 v47, v44, v44
	v_fmac_f32_e32 v47, v45, v45
	v_fmac_f32_e32 v47, v46, v46
	s_nop 1
	v_add_f32_dpp v47, v47, v47 quad_perm:[1,0,3,2] row_mask:0xf bank_mask:0xf bound_ctrl:1
	s_nop 1
	v_add_f32_dpp v47, v47, v47 quad_perm:[2,3,0,1] row_mask:0xf bank_mask:0xf bound_ctrl:1
	s_nop 1
	v_add_f32_dpp v47, v47, v47 row_half_mirror row_mask:0xf bank_mask:0xf bound_ctrl:1
	s_nop 1
	v_add_f32_dpp v47, v47, v47 row_mirror row_mask:0xf bank_mask:0xf bound_ctrl:1
	s_nop 0
	v_readlane_b32 s60, v47, 16
	v_readlane_b32 s61, v47, 48
	v_readlane_b32 s62, v47, 0
	v_readlane_b32 s63, v47, 32
	v_mov_b32_e32 v48, s60
	v_mov_b32_e32 v49, s61
	v_pk_add_f32 v[48:49], s[62:63], v[48:49]
	s_nop 0
	v_add_f32_e32 v47, v48, v49
	v_fmamk_f32 v47, v47, 0x3baaaaab, v9
	v_rsq_f32_e32 v47, v47
	s_nop 0
	v_mul_f32_e32 v44, v44, v47
	v_mul_f32_e32 v45, v45, v47
	v_mul_f32_e32 v46, v46, v47
	v_mul_f32_e32 v44, v44, v10
	v_mul_f32_e32 v45, v45, v11
	v_mul_f32_e32 v46, v46, v12
	v_mov_b32_e32 v48, v46
	s_nop 1
	v_permlane32_swap_b32_e32 v48, v46
	s_nop 1
	v_cndmask_b32_e64 v50, v46, v48, s[20:21]
	v_cndmask_b32_e64 v51, v48, v46, s[20:21]
	v_mul_f32_e32 v46, v50, v16
	v_fmac_f32_e32 v46, v51, v19
	v_cvt_pk_bf16_f32 v44, v44, v45
	v_cvt_pk_bf16_f32 v46, v46, v46
	ds_write_b16 v2, v44 offset:11520
	ds_write_b16_d16_hi v2, v44 offset:11648
	ds_write_b16 v2, v46 offset:11776
	ds_read_u16 v44, v2 offset:5760
	ds_read_u16 v45, v2 offset:5888
	ds_read_u16 v46, v2 offset:6016
	s_waitcnt lgkmcnt(0)
	v_lshlrev_b32_e32 v44, 16, v44
	v_lshlrev_b32_e32 v45, 16, v45
	v_lshlrev_b32_e32 v46, 16, v46
	v_mul_f32_e32 v47, v44, v44
	v_fmac_f32_e32 v47, v45, v45
	v_fmac_f32_e32 v47, v46, v46
	s_nop 1
	v_add_f32_dpp v47, v47, v47 quad_perm:[1,0,3,2] row_mask:0xf bank_mask:0xf bound_ctrl:1
	s_nop 1
	v_add_f32_dpp v47, v47, v47 quad_perm:[2,3,0,1] row_mask:0xf bank_mask:0xf bound_ctrl:1
	s_nop 1
	v_add_f32_dpp v47, v47, v47 row_half_mirror row_mask:0xf bank_mask:0xf bound_ctrl:1
	s_nop 1
	v_add_f32_dpp v47, v47, v47 row_mirror row_mask:0xf bank_mask:0xf bound_ctrl:1
	s_nop 0
	v_readlane_b32 s60, v47, 16
	v_readlane_b32 s61, v47, 48
	v_readlane_b32 s62, v47, 0
	v_readlane_b32 s63, v47, 32
	v_mov_b32_e32 v48, s60
	v_mov_b32_e32 v49, s61
	v_pk_add_f32 v[48:49], s[62:63], v[48:49]
	s_nop 0
	v_add_f32_e32 v47, v48, v49
	v_fmamk_f32 v47, v47, 0x3baaaaab, v9
	v_rsq_f32_e32 v47, v47
	s_nop 0
	v_mul_f32_e32 v44, v44, v47
	v_mul_f32_e32 v45, v45, v47
	v_mul_f32_e32 v46, v46, v47
	v_mul_f32_e32 v44, v44, v10
	v_mul_f32_e32 v45, v45, v11
	v_mul_f32_e32 v46, v46, v12
	v_mov_b32_e32 v48, v46
	s_nop 1
	v_permlane32_swap_b32_e32 v48, v46
	s_nop 1
	v_cndmask_b32_e64 v50, v46, v48, s[20:21]
	v_cndmask_b32_e64 v51, v48, v46, s[20:21]
	v_mul_f32_e32 v46, v50, v16
	v_fmac_f32_e32 v46, v51, v19
	v_cvt_pk_bf16_f32 v44, v44, v45
	v_cvt_pk_bf16_f32 v46, v46, v46
	ds_write_b16 v2, v44 offset:11904
	ds_write_b16_d16_hi v2, v44 offset:12032
	ds_write_b16 v2, v46 offset:12160
	s_waitcnt lgkmcnt(0)
	ds_read_b128 v[20:23], v1 offset:6144
	ds_read_b128 v[24:27], v1 offset:7168
	ds_read_b128 v[28:31], v1 offset:8192
	ds_read_b128 v[32:35], v1 offset:9216
	ds_read_b128 v[36:39], v1 offset:10240
	ds_read_b128 v[40:43], v1 offset:11264
	s_waitcnt lgkmcnt(0)
	global_store_dwordx4 v6, v[20:23], s[36:37]
	global_store_dwordx4 v6, v[24:27], s[36:37] offset:1024
	global_store_dwordx4 v6, v[28:31], s[36:37] offset:2048
	global_store_dwordx4 v6, v[32:35], s[36:37] offset:3072
	global_store_dwordx4 v6, v[36:39], s[42:43]
	global_store_dwordx4 v6, v[40:43], s[42:43] offset:1024
	s_branch .Lp5n_next
.Lp5n_krow:
	s_sub_u32 s39, s10, 0x3000
	s_lshl_b32 s36, s39, 13
	s_add_u32 s36, s24, s36
	s_addc_u32 s37, s25, 0
	s_add_u32 s42, s36, 0x1000
	s_addc_u32 s43, s37, 0
	global_load_dwordx4 v[20:23], v5, s[36:37]
	global_load_dwordx4 v[24:27], v5, s[36:37] offset:2048
	global_load_dwordx4 v[28:31], v5, s[42:43]
	global_load_dwordx4 v[32:35], v5, s[42:43] offset:2048
	s_mul_i32 s48, s39, 0x1800
	s_add_u32 s48, s28, s48
	s_addc_u32 s49, s29, 0
	s_add_u32 s50, s48, 0x1000
	s_addc_u32 s51, s49, 0
	s_mov_b32 s38, -1
	s_mov_b64 s[52:53], s[26:27]
	s_lshl_b32 s54, s39, 8
	s_cmp_lt_u32 s39, 0x2000
	s_cbranch_scc1 .Lp5n_kpe_done
	s_sub_u32 s55, s39, 0x2000
	s_cmp_ge_u32 s55, 0x600
	s_cselect_b32 s56, 1, 0
	s_cmp_ge_u32 s55, 0xc00
	s_cselect_b32 s57, 1, 0
	s_add_u32 s56, s56, s57
	s_cmp_ge_u32 s55, 0x1200
	s_cselect_b32 s57, 1, 0
	s_add_u32 s56, s56, s57
	s_mul_i32 s57, s56, 0x600
	s_sub_u32 s57, s55, s57
	s_cmp_lt_u32 s57, 0x200
	s_cbranch_scc1 .Lp5n_kpe_ctx
	s_sub_u32 s38, s57, 0x200
	s_lshl_b32 s54, s56, 10
	s_add_u32 s54, s54, s38
	s_add_u32 s54, s54, 0x2000
	s_lshl_b32 s54, s54, 8
	s_branch .Lp5n_kpe_done
.Lp5n_kpe_ctx:
	s_mov_b64 s[52:53], s[18:19]
	s_lshl_b32 s54, s56, 9
	s_add_u32 s54, s54, s57
	s_lshl_b32 s54, s54, 8
.Lp5n_kpe_done:
	s_add_u32 s52, s52, s54
	s_addc_u32 s53, s53, 0
	global_load_dword v18, v3, s[52:53]
	v_mov_b32_e32 v16, 1.0
	v_mov_b32_e32 v17, 0
	s_cmp_lt_i32 s38, 0
	s_cbranch_scc1 .Lp5n_norope_k
	s_lshl_b32 s44, s38, 7
	s_add_u32 s46, s30, s44
	s_addc_u32 s47, s31, 0
	global_load_dword v16, v4, s[46:47]
	s_add_u32 s46, s34, s44
	s_addc_u32 s47, s35, 0
	global_load_dword v17, v4, s[46:47]
.Lp5n_norope_k:
	s_waitcnt vmcnt(0)
	v_xor_b32_e32 v19, 0x80000000, v17
	v_cndmask_b32_e64 v19, v17, v19, s[20:21]
	ds_write_b128 v1, v[20:23]
	ds_write_b128 v1, v[24:27] offset:1024
	ds_write_b128 v1, v[28:31] offset:2048
	ds_write_b128 v1, v[32:35] offset:3072
	s_waitcnt lgkmcnt(0)
	ds_read_u16 v44, v2 offset:0
	ds_read_u16 v45, v2 offset:128
	s_waitcnt lgkmcnt(0)
	v_lshlrev_b32_e32 v44, 16, v44
	v_lshlrev_b32_e32 v45, 16, v45
	v_mov_b32_e32 v46, v18
	v_mul_f32_e32 v47, v44, v44
	v_fmac_f32_e32 v47, v45, v45
	v_fmac_f32_e32 v47, v46, v46
	s_nop 1
	v_add_f32_dpp v47, v47, v47 quad_perm:[1,0,3,2] row_mask:0xf bank_mask:0xf bound_ctrl:1
	s_nop 1
	v_add_f32_dpp v47, v47, v47 quad_perm:[2,3,0,1] row_mask:0xf bank_mask:0xf bound_ctrl:1
	s_nop 1
	v_add_f32_dpp v47, v47, v47 row_half_mirror row_mask:0xf bank_mask:0xf bound_ctrl:1
	s_nop 1
	v_add_f32_dpp v47, v47, v47 row_mirror row_mask:0xf bank_mask:0xf bound_ctrl:1
	s_nop 0
	v_readlane_b32 s60, v47, 16
	v_readlane_b32 s61, v47, 48
	v_readlane_b32 s62, v47, 0
	v_readlane_b32 s63, v47, 32
	v_mov_b32_e32 v48, s60
	v_mov_b32_e32 v49, s61
	v_pk_add_f32 v[48:49], s[62:63], v[48:49]
	s_nop 0
	v_add_f32_e32 v47, v48, v49
	v_fmamk_f32 v47, v47, 0x3baaaaab, v9
	v_rsq_f32_e32 v47, v47
	s_nop 0
	v_mul_f32_e32 v44, v44, v47
	v_mul_f32_e32 v45, v45, v47
	v_mul_f32_e32 v46, v46, v47
	v_mul_f32_e32 v44, v44, v13
	v_mul_f32_e32 v45, v45, v14
	v_mul_f32_e32 v46, v46, v15
	v_mov_b32_e32 v48, v46
	s_nop 1
	v_permlane32_swap_b32_e32 v48, v46
	s_nop 1
	v_cndmask_b32_e64 v50, v46, v48, s[20:21]
	v_cndmask_b32_e64 v51, v48, v46, s[20:21]
	v_mul_f32_e32 v46, v50, v16
	v_fmac_f32_e32 v46, v51, v19
	v_cvt_pk_bf16_f32 v44, v44, v45
	v_cvt_pk_bf16_f32 v46, v46, v46
	ds_write_b16 v2, v44 offset:6144
	ds_write_b16_d16_hi v2, v44 offset:6272
	ds_write_b16 v2, v46 offset:6400
	ds_read_u16 v44, v2 offset:256
	ds_read_u16 v45, v2 offset:384
	s_waitcnt lgkmcnt(0)
	v_lshlrev_b32_e32 v44, 16, v44
	v_lshlrev_b32_e32 v45, 16, v45
	v_mov_b32_e32 v46, v18
	v_mul_f32_e32 v47, v44, v44
	v_fmac_f32_e32 v47, v45, v45
	v_fmac_f32_e32 v47, v46, v46
	s_nop 1
	v_add_f32_dpp v47, v47, v47 quad_perm:[1,0,3,2] row_mask:0xf bank_mask:0xf bound_ctrl:1
	s_nop 1
	v_add_f32_dpp v47, v47, v47 quad_perm:[2,3,0,1] row_mask:0xf bank_mask:0xf bound_ctrl:1
	s_nop 1
	v_add_f32_dpp v47, v47, v47 row_half_mirror row_mask:0xf bank_mask:0xf bound_ctrl:1
	s_nop 1
	v_add_f32_dpp v47, v47, v47 row_mirror row_mask:0xf bank_mask:0xf bound_ctrl:1
	s_nop 0
	v_readlane_b32 s60, v47, 16
	v_readlane_b32 s61, v47, 48
	v_readlane_b32 s62, v47, 0
	v_readlane_b32 s63, v47, 32
	v_mov_b32_e32 v48, s60
	v_mov_b32_e32 v49, s61
	v_pk_add_f32 v[48:49], s[62:63], v[48:49]
	s_nop 0
	v_add_f32_e32 v47, v48, v49
	v_fmamk_f32 v47, v47, 0x3baaaaab, v9
	v_rsq_f32_e32 v47, v47
	s_nop 0
	v_mul_f32_e32 v44, v44, v47
	v_mul_f32_e32 v45, v45, v47
	v_mul_f32_e32 v46, v46, v47
	v_mul_f32_e32 v44, v44, v13
	v_mul_f32_e32 v45, v45, v14
	v_mul_f32_e32 v46, v46, v15
	v_mov_b32_e32 v48, v46
	s_nop 1
	v_permlane32_swap_b32_e32 v48, v46
	s_nop 1
	v_cndmask_b32_e64 v50, v46, v48, s[20:21]
	v_cndmask_b32_e64 v51, v48, v46, s[20:21]
	v_mul_f32_e32 v46, v50, v16
	v_fmac_f32_e32 v46, v51, v19
	v_cvt_pk_bf16_f32 v44, v44, v45
	v_cvt_pk_bf16_f32 v46, v46, v46
	ds_write_b16 v2, v44 offset:6528
	ds_write_b16_d16_hi v2, v44 offset:6656
	ds_write_b16 v2, v46 offset:6784
	ds_read_u16 v44, v2 offset:512
	ds_read_u16 v45, v2 offset:640
	s_waitcnt lgkmcnt(0)
	v_lshlrev_b32_e32 v44, 16, v44
	v_lshlrev_b32_e32 v45, 16, v45
	v_mov_b32_e32 v46, v18
	v_mul_f32_e32 v47, v44, v44
	v_fmac_f32_e32 v47, v45, v45
	v_fmac_f32_e32 v47, v46, v46
	s_nop 1
	v_add_f32_dpp v47, v47, v47 quad_perm:[1,0,3,2] row_mask:0xf bank_mask:0xf bound_ctrl:1
	s_nop 1
	v_add_f32_dpp v47, v47, v47 quad_perm:[2,3,0,1] row_mask:0xf bank_mask:0xf bound_ctrl:1
	s_nop 1
	v_add_f32_dpp v47, v47, v47 row_half_mirror row_mask:0xf bank_mask:0xf bound_ctrl:1
	s_nop 1
	v_add_f32_dpp v47, v47, v47 row_mirror row_mask:0xf bank_mask:0xf bound_ctrl:1
	s_nop 0
	v_readlane_b32 s60, v47, 16
	v_readlane_b32 s61, v47, 48
	v_readlane_b32 s62, v47, 0
	v_readlane_b32 s63, v47, 32
	v_mov_b32_e32 v48, s60
	v_mov_b32_e32 v49, s61
	v_pk_add_f32 v[48:49], s[62:63], v[48:49]
	s_nop 0
	v_add_f32_e32 v47, v48, v49
	v_fmamk_f32 v47, v47, 0x3baaaaab, v9
	v_rsq_f32_e32 v47, v47
	s_nop 0
	v_mul_f32_e32 v44, v44, v47
	v_mul_f32_e32 v45, v45, v47
	v_mul_f32_e32 v46, v46, v47
	v_mul_f32_e32 v44, v44, v13
	v_mul_f32_e32 v45, v45, v14
	v_mul_f32_e32 v46, v46, v15
	v_mov_b32_e32 v48, v46
	s_nop 1
	v_permlane32_swap_b32_e32 v48, v46
	s_nop 1
	v_cndmask_b32_e64 v50, v46, v48, s[20:21]
	v_cndmask_b32_e64 v51, v48, v46, s[20:21]
	v_mul_f32_e32 v46, v50, v16
	v_fmac_f32_e32 v46, v51, v19
	v_cvt_pk_bf16_f32 v44, v44, v45
	v_cvt_pk_bf16_f32 v46, v46, v46
	ds_write_b16 v2, v44 offset:6912
	ds_write_b16_d16_hi v2, v44 offset:7040
	ds_write_b16 v2, v46 offset:7168
	ds_read_u16 v44, v2 offset:768
	ds_read_u16 v45, v2 offset:896
	s_waitcnt lgkmcnt(0)
	v_lshlrev_b32_e32 v44, 16, v44
	v_lshlrev_b32_e32 v45, 16, v45
	v_mov_b32_e32 v46, v18
	v_mul_f32_e32 v47, v44, v44
	v_fmac_f32_e32 v47, v45, v45
	v_fmac_f32_e32 v47, v46, v46
	s_nop 1
	v_add_f32_dpp v47, v47, v47 quad_perm:[1,0,3,2] row_mask:0xf bank_mask:0xf bound_ctrl:1
	s_nop 1
	v_add_f32_dpp v47, v47, v47 quad_perm:[2,3,0,1] row_mask:0xf bank_mask:0xf bound_ctrl:1
	s_nop 1
	v_add_f32_dpp v47, v47, v47 row_half_mirror row_mask:0xf bank_mask:0xf bound_ctrl:1
	s_nop 1
	v_add_f32_dpp v47, v47, v47 row_mirror row_mask:0xf bank_mask:0xf bound_ctrl:1
	s_nop 0
	v_readlane_b32 s60, v47, 16
	v_readlane_b32 s61, v47, 48
	v_readlane_b32 s62, v47, 0
	v_readlane_b32 s63, v47, 32
	v_mov_b32_e32 v48, s60
	v_mov_b32_e32 v49, s61
	v_pk_add_f32 v[48:49], s[62:63], v[48:49]
	s_nop 0
	v_add_f32_e32 v47, v48, v49
	v_fmamk_f32 v47, v47, 0x3baaaaab, v9
	v_rsq_f32_e32 v47, v47
	s_nop 0
	v_mul_f32_e32 v44, v44, v47
	v_mul_f32_e32 v45, v45, v47
	v_mul_f32_e32 v46, v46, v47
	v_mul_f32_e32 v44, v44, v13
	v_mul_f32_e32 v45, v45, v14
	v_mul_f32_e32 v46, v46, v15
	v_mov_b32_e32 v48, v46
	s_nop 1
	v_permlane32_swap_b32_e32 v48, v46
	s_nop 1
	v_cndmask_b32_e64 v50, v46, v48, s[20:21]
	v_cndmask_b32_e64 v51, v48, v46, s[20:21]
	v_mul_f32_e32 v46, v50, v16
	v_fmac_f32_e32 v46, v51, v19
	v_cvt_pk_bf16_f32 v44, v44, v45
	v_cvt_pk_bf16_f32 v46, v46, v46
	ds_write_b16 v2, v44 offset:7296
	ds_write_b16_d16_hi v2, v44 offset:7424
	ds_write_b16 v2, v46 offset:7552
	ds_read_u16 v44, v2 offset:1024
	ds_read_u16 v45, v2 offset:1152
	s_waitcnt lgkmcnt(0)
	v_lshlrev_b32_e32 v44, 16, v44
	v_lshlrev_b32_e32 v45, 16, v45
	v_mov_b32_e32 v46, v18
	v_mul_f32_e32 v47, v44, v44
	v_fmac_f32_e32 v47, v45, v45
	v_fmac_f32_e32 v47, v46, v46
	s_nop 1
	v_add_f32_dpp v47, v47, v47 quad_perm:[1,0,3,2] row_mask:0xf bank_mask:0xf bound_ctrl:1
	s_nop 1
	v_add_f32_dpp v47, v47, v47 quad_perm:[2,3,0,1] row_mask:0xf bank_mask:0xf bound_ctrl:1
	s_nop 1
	v_add_f32_dpp v47, v47, v47 row_half_mirror row_mask:0xf bank_mask:0xf bound_ctrl:1
	s_nop 1
	v_add_f32_dpp v47, v47, v47 row_mirror row_mask:0xf bank_mask:0xf bound_ctrl:1
	s_nop 0
	v_readlane_b32 s60, v47, 16
	v_readlane_b32 s61, v47, 48
	v_readlane_b32 s62, v47, 0
	v_readlane_b32 s63, v47, 32
	v_mov_b32_e32 v48, s60
	v_mov_b32_e32 v49, s61
	v_pk_add_f32 v[48:49], s[62:63], v[48:49]
	s_nop 0
	v_add_f32_e32 v47, v48, v49
	v_fmamk_f32 v47, v47, 0x3baaaaab, v9
	v_rsq_f32_e32 v47, v47
	s_nop 0
	v_mul_f32_e32 v44, v44, v47
	v_mul_f32_e32 v45, v45, v47
	v_mul_f32_e32 v46, v46, v47
	v_mul_f32_e32 v44, v44, v13
	v_mul_f32_e32 v45, v45, v14
	v_mul_f32_e32 v46, v46, v15
	v_mov_b32_e32 v48, v46
	s_nop 1
	v_permlane32_swap_b32_e32 v48, v46
	s_nop 1
	v_cndmask_b32_e64 v50, v46, v48, s[20:21]
	v_cndmask_b32_e64 v51, v48, v46, s[20:21]
	v_mul_f32_e32 v46, v50, v16
	v_fmac_f32_e32 v46, v51, v19
	v_cvt_pk_bf16_f32 v44, v44, v45
	v_cvt_pk_bf16_f32 v46, v46, v46
	ds_write_b16 v2, v44 offset:7680
	ds_write_b16_d16_hi v2, v44 offset:7808
	ds_write_b16 v2, v46 offset:7936
	ds_read_u16 v44, v2 offset:1280
	ds_read_u16 v45, v2 offset:1408
	s_waitcnt lgkmcnt(0)
	v_lshlrev_b32_e32 v44, 16, v44
	v_lshlrev_b32_e32 v45, 16, v45
	v_mov_b32_e32 v46, v18
	v_mul_f32_e32 v47, v44, v44
	v_fmac_f32_e32 v47, v45, v45
	v_fmac_f32_e32 v47, v46, v46
	s_nop 1
	v_add_f32_dpp v47, v47, v47 quad_perm:[1,0,3,2] row_mask:0xf bank_mask:0xf bound_ctrl:1
	s_nop 1
	v_add_f32_dpp v47, v47, v47 quad_perm:[2,3,0,1] row_mask:0xf bank_mask:0xf bound_ctrl:1
	s_nop 1
	v_add_f32_dpp v47, v47, v47 row_half_mirror row_mask:0xf bank_mask:0xf bound_ctrl:1
	s_nop 1
	v_add_f32_dpp v47, v47, v47 row_mirror row_mask:0xf bank_mask:0xf bound_ctrl:1
	s_nop 0
	v_readlane_b32 s60, v47, 16
	v_readlane_b32 s61, v47, 48
	v_readlane_b32 s62, v47, 0
	v_readlane_b32 s63, v47, 32
	v_mov_b32_e32 v48, s60
	v_mov_b32_e32 v49, s61
	v_pk_add_f32 v[48:49], s[62:63], v[48:49]
	s_nop 0
	v_add_f32_e32 v47, v48, v49
	v_fmamk_f32 v47, v47, 0x3baaaaab, v9
	v_rsq_f32_e32 v47, v47
	s_nop 0
	v_mul_f32_e32 v44, v44, v47
	v_mul_f32_e32 v45, v45, v47
	v_mul_f32_e32 v46, v46, v47
	v_mul_f32_e32 v44, v44, v13
	v_mul_f32_e32 v45, v45, v14
	v_mul_f32_e32 v46, v46, v15
	v_mov_b32_e32 v48, v46
	s_nop 1
	v_permlane32_swap_b32_e32 v48, v46
	s_nop 1
	v_cndmask_b32_e64 v50, v46, v48, s[20:21]
	v_cndmask_b32_e64 v51, v48, v46, s[20:21]
	v_mul_f32_e32 v46, v50, v16
	v_fmac_f32_e32 v46, v51, v19
	v_cvt_pk_bf16_f32 v44, v44, v45
	v_cvt_pk_bf16_f32 v46, v46, v46
	ds_write_b16 v2, v44 offset:8064
	ds_write_b16_d16_hi v2, v44 offset:8192
	ds_write_b16 v2, v46 offset:8320
	ds_read_u16 v44, v2 offset:1536
	ds_read_u16 v45, v2 offset:1664
	s_waitcnt lgkmcnt(0)
	v_lshlrev_b32_e32 v44, 16, v44
	v_lshlrev_b32_e32 v45, 16, v45
	v_mov_b32_e32 v46, v18
	v_mul_f32_e32 v47, v44, v44
	v_fmac_f32_e32 v47, v45, v45
	v_fmac_f32_e32 v47, v46, v46
	s_nop 1
	v_add_f32_dpp v47, v47, v47 quad_perm:[1,0,3,2] row_mask:0xf bank_mask:0xf bound_ctrl:1
	s_nop 1
	v_add_f32_dpp v47, v47, v47 quad_perm:[2,3,0,1] row_mask:0xf bank_mask:0xf bound_ctrl:1
	s_nop 1
	v_add_f32_dpp v47, v47, v47 row_half_mirror row_mask:0xf bank_mask:0xf bound_ctrl:1
	s_nop 1
	v_add_f32_dpp v47, v47, v47 row_mirror row_mask:0xf bank_mask:0xf bound_ctrl:1
	s_nop 0
	v_readlane_b32 s60, v47, 16
	v_readlane_b32 s61, v47, 48
	v_readlane_b32 s62, v47, 0
	v_readlane_b32 s63, v47, 32
	v_mov_b32_e32 v48, s60
	v_mov_b32_e32 v49, s61
	v_pk_add_f32 v[48:49], s[62:63], v[48:49]
	s_nop 0
	v_add_f32_e32 v47, v48, v49
	v_fmamk_f32 v47, v47, 0x3baaaaab, v9
	v_rsq_f32_e32 v47, v47
	s_nop 0
	v_mul_f32_e32 v44, v44, v47
	v_mul_f32_e32 v45, v45, v47
	v_mul_f32_e32 v46, v46, v47
	v_mul_f32_e32 v44, v44, v13
	v_mul_f32_e32 v45, v45, v14
	v_mul_f32_e32 v46, v46, v15
	v_mov_b32_e32 v48, v46
	s_nop 1
	v_permlane32_swap_b32_e32 v48, v46
	s_nop 1
	v_cndmask_b32_e64 v50, v46, v48, s[20:21]
	v_cndmask_b32_e64 v51, v48, v46, s[20:21]
	v_mul_f32_e32 v46, v50, v16
	v_fmac_f32_e32 v46, v51, v19
	v_cvt_pk_bf16_f32 v44, v44, v45
	v_cvt_pk_bf16_f32 v46, v46, v46
	ds_write_b16 v2, v44 offset:8448
	ds_write_b16_d16_hi v2, v44 offset:8576
	ds_write_b16 v2, v46 offset:8704
	ds_read_u16 v44, v2 offset:1792
	ds_read_u16 v45, v2 offset:1920
	s_waitcnt lgkmcnt(0)
	v_lshlrev_b32_e32 v44, 16, v44
	v_lshlrev_b32_e32 v45, 16, v45
	v_mov_b32_e32 v46, v18
	v_mul_f32_e32 v47, v44, v44
	v_fmac_f32_e32 v47, v45, v45
	v_fmac_f32_e32 v47, v46, v46
	s_nop 1
	v_add_f32_dpp v47, v47, v47 quad_perm:[1,0,3,2] row_mask:0xf bank_mask:0xf bound_ctrl:1
	s_nop 1
	v_add_f32_dpp v47, v47, v47 quad_perm:[2,3,0,1] row_mask:0xf bank_mask:0xf bound_ctrl:1
	s_nop 1
	v_add_f32_dpp v47, v47, v47 row_half_mirror row_mask:0xf bank_mask:0xf bound_ctrl:1
	s_nop 1
	v_add_f32_dpp v47, v47, v47 row_mirror row_mask:0xf bank_mask:0xf bound_ctrl:1
	s_nop 0
	v_readlane_b32 s60, v47, 16
	v_readlane_b32 s61, v47, 48
	v_readlane_b32 s62, v47, 0
	v_readlane_b32 s63, v47, 32
	v_mov_b32_e32 v48, s60
	v_mov_b32_e32 v49, s61
	v_pk_add_f32 v[48:49], s[62:63], v[48:49]
	s_nop 0
	v_add_f32_e32 v47, v48, v49
	v_fmamk_f32 v47, v47, 0x3baaaaab, v9
	v_rsq_f32_e32 v47, v47
	s_nop 0
	v_mul_f32_e32 v44, v44, v47
	v_mul_f32_e32 v45, v45, v47
	v_mul_f32_e32 v46, v46, v47
	v_mul_f32_e32 v44, v44, v13
	v_mul_f32_e32 v45, v45, v14
	v_mul_f32_e32 v46, v46, v15
	v_mov_b32_e32 v48, v46
	s_nop 1
	v_permlane32_swap_b32_e32 v48, v46
	s_nop 1
	v_cndmask_b32_e64 v50, v46, v48, s[20:21]
	v_cndmask_b32_e64 v51, v48, v46, s[20:21]
	v_mul_f32_e32 v46, v50, v16
	v_fmac_f32_e32 v46, v51, v19
	v_cvt_pk_bf16_f32 v44, v44, v45
	v_cvt_pk_bf16_f32 v46, v46, v46
	ds_write_b16 v2, v44 offset:8832
	ds_write_b16_d16_hi v2, v44 offset:8960
	ds_write_b16 v2, v46 offset:9088
	ds_read_u16 v44, v2 offset:2048
	ds_read_u16 v45, v2 offset:2176
	s_waitcnt lgkmcnt(0)
	v_lshlrev_b32_e32 v44, 16, v44
	v_lshlrev_b32_e32 v45, 16, v45
	v_mov_b32_e32 v46, v18
	v_mul_f32_e32 v47, v44, v44
	v_fmac_f32_e32 v47, v45, v45
	v_fmac_f32_e32 v47, v46, v46
	s_nop 1
	v_add_f32_dpp v47, v47, v47 quad_perm:[1,0,3,2] row_mask:0xf bank_mask:0xf bound_ctrl:1
	s_nop 1
	v_add_f32_dpp v47, v47, v47 quad_perm:[2,3,0,1] row_mask:0xf bank_mask:0xf bound_ctrl:1
	s_nop 1
	v_add_f32_dpp v47, v47, v47 row_half_mirror row_mask:0xf bank_mask:0xf bound_ctrl:1
	s_nop 1
	v_add_f32_dpp v47, v47, v47 row_mirror row_mask:0xf bank_mask:0xf bound_ctrl:1
	s_nop 0
	v_readlane_b32 s60, v47, 16
	v_readlane_b32 s61, v47, 48
	v_readlane_b32 s62, v47, 0
	v_readlane_b32 s63, v47, 32
	v_mov_b32_e32 v48, s60
	v_mov_b32_e32 v49, s61
	v_pk_add_f32 v[48:49], s[62:63], v[48:49]
	s_nop 0
	v_add_f32_e32 v47, v48, v49
	v_fmamk_f32 v47, v47, 0x3baaaaab, v9
	v_rsq_f32_e32 v47, v47
	s_nop 0
	v_mul_f32_e32 v44, v44, v47
	v_mul_f32_e32 v45, v45, v47
	v_mul_f32_e32 v46, v46, v47
	v_mul_f32_e32 v44, v44, v13
	v_mul_f32_e32 v45, v45, v14
	v_mul_f32_e32 v46, v46, v15
	v_mov_b32_e32 v48, v46
	s_nop 1
	v_permlane32_swap_b32_e32 v48, v46
	s_nop 1
	v_cndmask_b32_e64 v50, v46, v48, s[20:21]
	v_cndmask_b32_e64 v51, v48, v46, s[20:21]
	v_mul_f32_e32 v46, v50, v16
	v_fmac_f32_e32 v46, v51, v19
	v_cvt_pk_bf16_f32 v44, v44, v45
	v_cvt_pk_bf16_f32 v46, v46, v46
	ds_write_b16 v2, v44 offset:9216
	ds_write_b16_d16_hi v2, v44 offset:9344
	ds_write_b16 v2, v46 offset:9472
	ds_read_u16 v44, v2 offset:2304
	ds_read_u16 v45, v2 offset:2432
	s_waitcnt lgkmcnt(0)
	v_lshlrev_b32_e32 v44, 16, v44
	v_lshlrev_b32_e32 v45, 16, v45
	v_mov_b32_e32 v46, v18
	v_mul_f32_e32 v47, v44, v44
	v_fmac_f32_e32 v47, v45, v45
	v_fmac_f32_e32 v47, v46, v46
	s_nop 1
	v_add_f32_dpp v47, v47, v47 quad_perm:[1,0,3,2] row_mask:0xf bank_mask:0xf bound_ctrl:1
	s_nop 1
	v_add_f32_dpp v47, v47, v47 quad_perm:[2,3,0,1] row_mask:0xf bank_mask:0xf bound_ctrl:1
	s_nop 1
	v_add_f32_dpp v47, v47, v47 row_half_mirror row_mask:0xf bank_mask:0xf bound_ctrl:1
	s_nop 1
	v_add_f32_dpp v47, v47, v47 row_mirror row_mask:0xf bank_mask:0xf bound_ctrl:1
	s_nop 0
	v_readlane_b32 s60, v47, 16
	v_readlane_b32 s61, v47, 48
	v_readlane_b32 s62, v47, 0
	v_readlane_b32 s63, v47, 32
	v_mov_b32_e32 v48, s60
	v_mov_b32_e32 v49, s61
	v_pk_add_f32 v[48:49], s[62:63], v[48:49]
	s_nop 0
	v_add_f32_e32 v47, v48, v49
	v_fmamk_f32 v47, v47, 0x3baaaaab, v9
	v_rsq_f32_e32 v47, v47
	s_nop 0
	v_mul_f32_e32 v44, v44, v47
	v_mul_f32_e32 v45, v45, v47
	v_mul_f32_e32 v46, v46, v47
	v_mul_f32_e32 v44, v44, v13
	v_mul_f32_e32 v45, v45, v14
	v_mul_f32_e32 v46, v46, v15
	v_mov_b32_e32 v48, v46
	s_nop 1
	v_permlane32_swap_b32_e32 v48, v46
	s_nop 1
	v_cndmask_b32_e64 v50, v46, v48, s[20:21]
	v_cndmask_b32_e64 v51, v48, v46, s[20:21]
	v_mul_f32_e32 v46, v50, v16
	v_fmac_f32_e32 v46, v51, v19
	v_cvt_pk_bf16_f32 v44, v44, v45
	v_cvt_pk_bf16_f32 v46, v46, v46
	ds_write_b16 v2, v44 offset:9600
	ds_write_b16_d16_hi v2, v44 offset:9728
	ds_write_b16 v2, v46 offset:9856
	ds_read_u16 v44, v2 offset:2560
	ds_read_u16 v45, v2 offset:2688
	s_waitcnt lgkmcnt(0)
	v_lshlrev_b32_e32 v44, 16, v44
	v_lshlrev_b32_e32 v45, 16, v45
	v_mov_b32_e32 v46, v18
	v_mul_f32_e32 v47, v44, v44
	v_fmac_f32_e32 v47, v45, v45
	v_fmac_f32_e32 v47, v46, v46
	s_nop 1
	v_add_f32_dpp v47, v47, v47 quad_perm:[1,0,3,2] row_mask:0xf bank_mask:0xf bound_ctrl:1
	s_nop 1
	v_add_f32_dpp v47, v47, v47 quad_perm:[2,3,0,1] row_mask:0xf bank_mask:0xf bound_ctrl:1
	s_nop 1
	v_add_f32_dpp v47, v47, v47 row_half_mirror row_mask:0xf bank_mask:0xf bound_ctrl:1
	s_nop 1
	v_add_f32_dpp v47, v47, v47 row_mirror row_mask:0xf bank_mask:0xf bound_ctrl:1
	s_nop 0
	v_readlane_b32 s60, v47, 16
	v_readlane_b32 s61, v47, 48
	v_readlane_b32 s62, v47, 0
	v_readlane_b32 s63, v47, 32
	v_mov_b32_e32 v48, s60
	v_mov_b32_e32 v49, s61
	v_pk_add_f32 v[48:49], s[62:63], v[48:49]
	s_nop 0
	v_add_f32_e32 v47, v48, v49
	v_fmamk_f32 v47, v47, 0x3baaaaab, v9
	v_rsq_f32_e32 v47, v47
	s_nop 0
	v_mul_f32_e32 v44, v44, v47
	v_mul_f32_e32 v45, v45, v47
	v_mul_f32_e32 v46, v46, v47
	v_mul_f32_e32 v44, v44, v13
	v_mul_f32_e32 v45, v45, v14
	v_mul_f32_e32 v46, v46, v15
	v_mov_b32_e32 v48, v46
	s_nop 1
	v_permlane32_swap_b32_e32 v48, v46
	s_nop 1
	v_cndmask_b32_e64 v50, v46, v48, s[20:21]
	v_cndmask_b32_e64 v51, v48, v46, s[20:21]
	v_mul_f32_e32 v46, v50, v16
	v_fmac_f32_e32 v46, v51, v19
	v_cvt_pk_bf16_f32 v44, v44, v45
	v_cvt_pk_bf16_f32 v46, v46, v46
	ds_write_b16 v2, v44 offset:9984
	ds_write_b16_d16_hi v2, v44 offset:10112
	ds_write_b16 v2, v46 offset:10240
	ds_read_u16 v44, v2 offset:2816
	ds_read_u16 v45, v2 offset:2944
	s_waitcnt lgkmcnt(0)
	v_lshlrev_b32_e32 v44, 16, v44
	v_lshlrev_b32_e32 v45, 16, v45
	v_mov_b32_e32 v46, v18
	v_mul_f32_e32 v47, v44, v44
	v_fmac_f32_e32 v47, v45, v45
	v_fmac_f32_e32 v47, v46, v46
	s_nop 1
	v_add_f32_dpp v47, v47, v47 quad_perm:[1,0,3,2] row_mask:0xf bank_mask:0xf bound_ctrl:1
	s_nop 1
	v_add_f32_dpp v47, v47, v47 quad_perm:[2,3,0,1] row_mask:0xf bank_mask:0xf bound_ctrl:1
	s_nop 1
	v_add_f32_dpp v47, v47, v47 row_half_mirror row_mask:0xf bank_mask:0xf bound_ctrl:1
	s_nop 1
	v_add_f32_dpp v47, v47, v47 row_mirror row_mask:0xf bank_mask:0xf bound_ctrl:1
	s_nop 0
	v_readlane_b32 s60, v47, 16
	v_readlane_b32 s61, v47, 48
	v_readlane_b32 s62, v47, 0
	v_readlane_b32 s63, v47, 32
	v_mov_b32_e32 v48, s60
	v_mov_b32_e32 v49, s61
	v_pk_add_f32 v[48:49], s[62:63], v[48:49]
	s_nop 0
	v_add_f32_e32 v47, v48, v49
	v_fmamk_f32 v47, v47, 0x3baaaaab, v9
	v_rsq_f32_e32 v47, v47
	s_nop 0
	v_mul_f32_e32 v44, v44, v47
	v_mul_f32_e32 v45, v45, v47
	v_mul_f32_e32 v46, v46, v47
	v_mul_f32_e32 v44, v44, v13
	v_mul_f32_e32 v45, v45, v14
	v_mul_f32_e32 v46, v46, v15
	v_mov_b32_e32 v48, v46
	s_nop 1
	v_permlane32_swap_b32_e32 v48, v46
	s_nop 1
	v_cndmask_b32_e64 v50, v46, v48, s[20:21]
	v_cndmask_b32_e64 v51, v48, v46, s[20:21]
	v_mul_f32_e32 v46, v50, v16
	v_fmac_f32_e32 v46, v51, v19
	v_cvt_pk_bf16_f32 v44, v44, v45
	v_cvt_pk_bf16_f32 v46, v46, v46
	ds_write_b16 v2, v44 offset:10368
	ds_write_b16_d16_hi v2, v44 offset:10496
	ds_write_b16 v2, v46 offset:10624
	ds_read_u16 v44, v2 offset:3072
	ds_read_u16 v45, v2 offset:3200
	s_waitcnt lgkmcnt(0)
	v_lshlrev_b32_e32 v44, 16, v44
	v_lshlrev_b32_e32 v45, 16, v45
	v_mov_b32_e32 v46, v18
	v_mul_f32_e32 v47, v44, v44
	v_fmac_f32_e32 v47, v45, v45
	v_fmac_f32_e32 v47, v46, v46
	s_nop 1
	v_add_f32_dpp v47, v47, v47 quad_perm:[1,0,3,2] row_mask:0xf bank_mask:0xf bound_ctrl:1
	s_nop 1
	v_add_f32_dpp v47, v47, v47 quad_perm:[2,3,0,1] row_mask:0xf bank_mask:0xf bound_ctrl:1
	s_nop 1
	v_add_f32_dpp v47, v47, v47 row_half_mirror row_mask:0xf bank_mask:0xf bound_ctrl:1
	s_nop 1
	v_add_f32_dpp v47, v47, v47 row_mirror row_mask:0xf bank_mask:0xf bound_ctrl:1
	s_nop 0
	v_readlane_b32 s60, v47, 16
	v_readlane_b32 s61, v47, 48
	v_readlane_b32 s62, v47, 0
	v_readlane_b32 s63, v47, 32
	v_mov_b32_e32 v48, s60
	v_mov_b32_e32 v49, s61
	v_pk_add_f32 v[48:49], s[62:63], v[48:49]
	s_nop 0
	v_add_f32_e32 v47, v48, v49
	v_fmamk_f32 v47, v47, 0x3baaaaab, v9
	v_rsq_f32_e32 v47, v47
	s_nop 0
	v_mul_f32_e32 v44, v44, v47
	v_mul_f32_e32 v45, v45, v47
	v_mul_f32_e32 v46, v46, v47
	v_mul_f32_e32 v44, v44, v13
	v_mul_f32_e32 v45, v45, v14
	v_mul_f32_e32 v46, v46, v15
	v_mov_b32_e32 v48, v46
	s_nop 1
	v_permlane32_swap_b32_e32 v48, v46
	s_nop 1
	v_cndmask_b32_e64 v50, v46, v48, s[20:21]
	v_cndmask_b32_e64 v51, v48, v46, s[20:21]
	v_mul_f32_e32 v46, v50, v16
	v_fmac_f32_e32 v46, v51, v19
	v_cvt_pk_bf16_f32 v44, v44, v45
	v_cvt_pk_bf16_f32 v46, v46, v46
	ds_write_b16 v2, v44 offset:10752
	ds_write_b16_d16_hi v2, v44 offset:10880
	ds_write_b16 v2, v46 offset:11008
	ds_read_u16 v44, v2 offset:3328
	ds_read_u16 v45, v2 offset:3456
	s_waitcnt lgkmcnt(0)
	v_lshlrev_b32_e32 v44, 16, v44
	v_lshlrev_b32_e32 v45, 16, v45
	v_mov_b32_e32 v46, v18
	v_mul_f32_e32 v47, v44, v44
	v_fmac_f32_e32 v47, v45, v45
	v_fmac_f32_e32 v47, v46, v46
	s_nop 1
	v_add_f32_dpp v47, v47, v47 quad_perm:[1,0,3,2] row_mask:0xf bank_mask:0xf bound_ctrl:1
	s_nop 1
	v_add_f32_dpp v47, v47, v47 quad_perm:[2,3,0,1] row_mask:0xf bank_mask:0xf bound_ctrl:1
	s_nop 1
	v_add_f32_dpp v47, v47, v47 row_half_mirror row_mask:0xf bank_mask:0xf bound_ctrl:1
	s_nop 1
	v_add_f32_dpp v47, v47, v47 row_mirror row_mask:0xf bank_mask:0xf bound_ctrl:1
	s_nop 0
	v_readlane_b32 s60, v47, 16
	v_readlane_b32 s61, v47, 48
	v_readlane_b32 s62, v47, 0
	v_readlane_b32 s63, v47, 32
	v_mov_b32_e32 v48, s60
	v_mov_b32_e32 v49, s61
	v_pk_add_f32 v[48:49], s[62:63], v[48:49]
	s_nop 0
	v_add_f32_e32 v47, v48, v49
	v_fmamk_f32 v47, v47, 0x3baaaaab, v9
	v_rsq_f32_e32 v47, v47
	s_nop 0
	v_mul_f32_e32 v44, v44, v47
	v_mul_f32_e32 v45, v45, v47
	v_mul_f32_e32 v46, v46, v47
	v_mul_f32_e32 v44, v44, v13
	v_mul_f32_e32 v45, v45, v14
	v_mul_f32_e32 v46, v46, v15
	v_mov_b32_e32 v48, v46
	s_nop 1
	v_permlane32_swap_b32_e32 v48, v46
	s_nop 1
	v_cndmask_b32_e64 v50, v46, v48, s[20:21]
	v_cndmask_b32_e64 v51, v48, v46, s[20:21]
	v_mul_f32_e32 v46, v50, v16
	v_fmac_f32_e32 v46, v51, v19
	v_cvt_pk_bf16_f32 v44, v44, v45
	v_cvt_pk_bf16_f32 v46, v46, v46
	ds_write_b16 v2, v44 offset:11136
	ds_write_b16_d16_hi v2, v44 offset:11264
	ds_write_b16 v2, v46 offset:11392
	ds_read_u16 v44, v2 offset:3584
	ds_read_u16 v45, v2 offset:3712
	s_waitcnt lgkmcnt(0)
	v_lshlrev_b32_e32 v44, 16, v44
	v_lshlrev_b32_e32 v45, 16, v45
	v_mov_b32_e32 v46, v18
	v_mul_f32_e32 v47, v44, v44
	v_fmac_f32_e32 v47, v45, v45
	v_fmac_f32_e32 v47, v46, v46
	s_nop 1
	v_add_f32_dpp v47, v47, v47 quad_perm:[1,0,3,2] row_mask:0xf bank_mask:0xf bound_ctrl:1
	s_nop 1
	v_add_f32_dpp v47, v47, v47 quad_perm:[2,3,0,1] row_mask:0xf bank_mask:0xf bound_ctrl:1
	s_nop 1
	v_add_f32_dpp v47, v47, v47 row_half_mirror row_mask:0xf bank_mask:0xf bound_ctrl:1
	s_nop 1
	v_add_f32_dpp v47, v47, v47 row_mirror row_mask:0xf bank_mask:0xf bound_ctrl:1
	s_nop 0
	v_readlane_b32 s60, v47, 16
	v_readlane_b32 s61, v47, 48
	v_readlane_b32 s62, v47, 0
	v_readlane_b32 s63, v47, 32
	v_mov_b32_e32 v48, s60
	v_mov_b32_e32 v49, s61
	v_pk_add_f32 v[48:49], s[62:63], v[48:49]
	s_nop 0
	v_add_f32_e32 v47, v48, v49
	v_fmamk_f32 v47, v47, 0x3baaaaab, v9
	v_rsq_f32_e32 v47, v47
	s_nop 0
	v_mul_f32_e32 v44, v44, v47
	v_mul_f32_e32 v45, v45, v47
	v_mul_f32_e32 v46, v46, v47
	v_mul_f32_e32 v44, v44, v13
	v_mul_f32_e32 v45, v45, v14
	v_mul_f32_e32 v46, v46, v15
	v_mov_b32_e32 v48, v46
	s_nop 1
	v_permlane32_swap_b32_e32 v48, v46
	s_nop 1
	v_cndmask_b32_e64 v50, v46, v48, s[20:21]
	v_cndmask_b32_e64 v51, v48, v46, s[20:21]
	v_mul_f32_e32 v46, v50, v16
	v_fmac_f32_e32 v46, v51, v19
	v_cvt_pk_bf16_f32 v44, v44, v45
	v_cvt_pk_bf16_f32 v46, v46, v46
	ds_write_b16 v2, v44 offset:11520
	ds_write_b16_d16_hi v2, v44 offset:11648
	ds_write_b16 v2, v46 offset:11776
	ds_read_u16 v44, v2 offset:3840
	ds_read_u16 v45, v2 offset:3968
	s_waitcnt lgkmcnt(0)
	v_lshlrev_b32_e32 v44, 16, v44
	v_lshlrev_b32_e32 v45, 16, v45
	v_mov_b32_e32 v46, v18
	v_mul_f32_e32 v47, v44, v44
	v_fmac_f32_e32 v47, v45, v45
	v_fmac_f32_e32 v47, v46, v46
	s_nop 1
	v_add_f32_dpp v47, v47, v47 quad_perm:[1,0,3,2] row_mask:0xf bank_mask:0xf bound_ctrl:1
	s_nop 1
	v_add_f32_dpp v47, v47, v47 quad_perm:[2,3,0,1] row_mask:0xf bank_mask:0xf bound_ctrl:1
	s_nop 1
	v_add_f32_dpp v47, v47, v47 row_half_mirror row_mask:0xf bank_mask:0xf bound_ctrl:1
	s_nop 1
	v_add_f32_dpp v47, v47, v47 row_mirror row_mask:0xf bank_mask:0xf bound_ctrl:1
	s_nop 0
	v_readlane_b32 s60, v47, 16
	v_readlane_b32 s61, v47, 48
	v_readlane_b32 s62, v47, 0
	v_readlane_b32 s63, v47, 32
	v_mov_b32_e32 v48, s60
	v_mov_b32_e32 v49, s61
	v_pk_add_f32 v[48:49], s[62:63], v[48:49]
	s_nop 0
	v_add_f32_e32 v47, v48, v49
	v_fmamk_f32 v47, v47, 0x3baaaaab, v9
	v_rsq_f32_e32 v47, v47
	s_nop 0
	v_mul_f32_e32 v44, v44, v47
	v_mul_f32_e32 v45, v45, v47
	v_mul_f32_e32 v46, v46, v47
	v_mul_f32_e32 v44, v44, v13
	v_mul_f32_e32 v45, v45, v14
	v_mul_f32_e32 v46, v46, v15
	v_mov_b32_e32 v48, v46
	s_nop 1
	v_permlane32_swap_b32_e32 v48, v46
	s_nop 1
	v_cndmask_b32_e64 v50, v46, v48, s[20:21]
	v_cndmask_b32_e64 v51, v48, v46, s[20:21]
	v_mul_f32_e32 v46, v50, v16
	v_fmac_f32_e32 v46, v51, v19
	v_cvt_pk_bf16_f32 v44, v44, v45
	v_cvt_pk_bf16_f32 v46, v46, v46
	ds_write_b16 v2, v44 offset:11904
	ds_write_b16_d16_hi v2, v44 offset:12032
	ds_write_b16 v2, v46 offset:12160
	s_waitcnt lgkmcnt(0)
	ds_read_b128 v[20:23], v1 offset:6144
	ds_read_b128 v[24:27], v1 offset:7168
	ds_read_b128 v[28:31], v1 offset:8192
	ds_read_b128 v[32:35], v1 offset:9216
	ds_read_b128 v[36:39], v1 offset:10240
	ds_read_b128 v[40:43], v1 offset:11264
	s_waitcnt lgkmcnt(0)
	global_store_dwordx4 v6, v[20:23], s[48:49]
	global_store_dwordx4 v6, v[24:27], s[48:49] offset:1024
	global_store_dwordx4 v6, v[28:31], s[48:49] offset:2048
	global_store_dwordx4 v6, v[32:35], s[48:49] offset:3072
	global_store_dwordx4 v6, v[36:39], s[50:51]
	global_store_dwordx4 v6, v[40:43], s[50:51] offset:1024
.Lp5n_next:
	s_add_u32 s10, s10, 0x800
	s_branch .Lp5n_loop
.Lp5n_done:
.LBB0_1000:
	s_cmp_gt_i32 s91, 6
	s_cselect_b64 s[0:1], -1, 0
	s_and_b64 s[2:3], s[8:9], s[0:1]
	s_andn2_b64 vcc, exec, s[2:3]
	s_cbranch_vccnz .LBB0_1050
	s_waitcnt vmcnt(0)
	v_cmp_eq_u32_e32 vcc, 0, v0
	s_waitcnt vmcnt(0) lgkmcnt(0)
	s_barrier
	s_and_saveexec_b64 s[2:3], vcc
	s_cbranch_execz .LBB0_1049
	v_readlane_b32 s4, v237, 37
	s_waitcnt vmcnt(0) expcnt(0) lgkmcnt(0)
	s_nop 0
	v_mov_b32_e32 v1, s4
	ds_read_b32 v3, v1
	ds_read_b32 v1, v1 offset:4
	s_waitcnt lgkmcnt(1)
	v_cmp_ne_u32_e32 vcc, 0, v3
	s_cbranch_vccnz .LBB0_1017
	v_readlane_b32 s4, v237, 0
	v_readlane_b32 s5, v237, 1
	s_load_dwordx2 s[8:9], s[4:5], 0x4
	s_add_u32 s4, s88, 0x4200
	s_addc_u32 s5, s89, 0
	s_add_u32 s6, s88, 0x4400
	s_addc_u32 s7, s89, 0
	s_waitcnt lgkmcnt(0)
	s_mul_i32 s48, s8, s33
	s_add_u32 s8, s88, 0x4500
	s_mul_i32 s48, s48, s9
	s_addc_u32 s9, s89, 0
	s_add_u32 s10, s88, 0x4600
	s_addc_u32 s11, s89, 0
	s_add_u32 s12, s88, 0x4700
	s_addc_u32 s13, s89, 0
	s_add_u32 s14, s88, 0x4800
	s_addc_u32 s15, s89, 0
	s_add_u32 s16, s88, 0x4900
	s_addc_u32 s17, s89, 0
	s_add_u32 s18, s88, 0x4a00
	s_addc_u32 s19, s89, 0
	s_add_u32 s20, s88, 0x4b00
	s_addc_u32 s21, s89, 0
	s_add_u32 s22, s88, 0x4c00
	s_addc_u32 s23, s89, 0
	s_add_u32 s24, s88, 0x4d00
	s_addc_u32 s25, s89, 0
	s_add_u32 s26, s88, 0x4e00
	s_addc_u32 s27, s89, 0
	s_add_u32 s28, s88, 0x4f00
	s_addc_u32 s29, s89, 0
	s_add_u32 s30, s88, 0x5000
	s_addc_u32 s31, s89, 0
	s_add_u32 s34, s88, 0x5100
	s_addc_u32 s35, s89, 0
	s_add_u32 s36, s88, 0x5200
	s_addc_u32 s37, s89, 0
	s_add_u32 s38, s88, 0x5300
	s_addc_u32 s39, s89, 0
	s_mov_b32 s49, 1
	v_mov_b32_e32 v17, 0
	s_branch .LBB0_1005
